# mixer A (SWA) mask lookups: batched unconditional LDS reads then one wait, instead of exec-masked serial lookups
# speedup vs baseline: 1.0271x; 1.0010x over previous
; template <int MODE>
; __device__ __forceinline__ void attn_wave(LAS unsigned char* lds, const bf16_t* qkv, bf16_t* Yout, const float* sinks, int wi) {
;     ...
;             const int dbase = q0 + QSTEP * qt + c - k0 - 4 * g;
;             if (MODE == MODE_A) {
;                 float mx = -1e30f;
; #pragma unroll
;                 for (int nt = 0; nt < 2; ++nt)
; #pragma unroll
;                     for (int j = 0; j < 4; ++j) { const int dist = dbase - (16 * nt + j); const bool valid = (unsigned)dist < 128u;
;                         const float bias2 = lutp[qt * HSTEP * 128 + (dist & 127)];
;                         const float lg = valid ? (s[nt][j] * C1 + bias2) : -1e30f; s[nt][j] = lg; mx = fmaxf(mx, lg); }
;                 mx = fmaxf(mx, __shfl_xor(mx, 16)); mx = fmaxf(mx, __shfl_xor(mx, 32));
;                 const float mnew = fmaxf(mrun[qt], mx); const float alpha = __builtin_amdgcn_exp2f(mrun[qt] - mnew); mrun[qt] = mnew;
;                 float ps = 0.f;
; #pragma unroll
;                 for (int nt = 0; nt < 2; ++nt)
; #pragma unroll
;                     for (int j = 0; j < 4; ++j) { const float p = __builtin_amdgcn_exp2f(s[nt][j] - mnew); s[nt][j] = p; ps += p; }
;                 lrun[qt] = lrun[qt] * alpha + ps;
; #pragma unroll
;                 for (int dt = 0; dt < 4; ++dt) o[qt][dt] = o[qt][dt] * alpha;
.LBB0_264:
	s_waitcnt vmcnt(3)
	v_mfma_f32_16x16x32_bf16 v[136:139], v[120:123], v[72:75], 0
	s_waitcnt vmcnt(2)
	v_mfma_f32_16x16x32_bf16 v[140:143], v[124:127], v[76:79], v[136:139]
	s_waitcnt vmcnt(1)
	v_mfma_f32_16x16x32_bf16 v[136:139], v[132:135], v[72:75], 0
	s_waitcnt vmcnt(0)
	v_mfma_f32_16x16x32_bf16 v[136:139], v[128:131], v[76:79], v[136:139]
	v_add_u32_e32 v228, s19, v167
	v_add_u32_e32 v228, 0x12000, v228
	ds_read_b32 v228, v228
	v_add_u32_e32 v229, s19, v165
	v_add_u32_e32 v229, 0x11ffc, v229
	ds_read_b32 v229, v229
	v_add_u32_e32 v230, s19, v165
	v_add_u32_e32 v230, 0x11ff8, v230
	ds_read_b32 v230, v230
	v_add_u32_e32 v231, s19, v165
	v_add_u32_e32 v231, 0x11ff4, v231
	ds_read_b32 v231, v231
	v_add_u32_e32 v232, s19, v165
	v_add_u32_e32 v232, 0x11fc0, v232
	ds_read_b32 v232, v232
	v_add_u32_e32 v233, s19, v165
	v_add_u32_e32 v233, 0x11fbc, v233
	ds_read_b32 v233, v233
	v_add_u32_e32 v234, s19, v165
	v_add_u32_e32 v234, 0x11fb8, v234
	ds_read_b32 v234, v234
	v_add_u32_e32 v235, s19, v165
	v_add_u32_e32 v235, 0x11fb4, v235
	ds_read_b32 v235, v235
	s_waitcnt lgkmcnt(0)
	v_cmp_gt_u32_e32 vcc, s15, v171
	v_fmac_f32_e32 v228, 0x3e38aa3b, v140
	s_nop 0
	v_cndmask_b32_e32 v173, v226, v228, vcc
	v_add_u32_e32 v236, 30, v170
	v_cmp_gt_u32_e32 vcc, s15, v236
	v_fmac_f32_e32 v229, 0x3e38aa3b, v141
	s_nop 0
	v_cndmask_b32_e32 v172, v226, v229, vcc
	v_add_u32_e32 v236, 29, v170
	v_cmp_gt_u32_e32 vcc, s15, v236
	v_fmac_f32_e32 v230, 0x3e38aa3b, v142
	s_nop 0
	v_cndmask_b32_e32 v141, v226, v230, vcc
	v_add_u32_e32 v236, 28, v170
	v_cmp_gt_u32_e32 vcc, s15, v236
	v_fmac_f32_e32 v231, 0x3e38aa3b, v143
	s_nop 0
	v_cndmask_b32_e32 v140, v226, v231, vcc
	v_add_u32_e32 v236, 15, v170
	v_cmp_gt_u32_e32 vcc, s15, v236
	v_fmac_f32_e32 v232, 0x3e38aa3b, v136
	s_nop 0
	v_cndmask_b32_e32 v143, v226, v232, vcc
	v_add_u32_e32 v236, 14, v170
	v_cmp_gt_u32_e32 vcc, s15, v236
	v_fmac_f32_e32 v233, 0x3e38aa3b, v137
	s_nop 0
	v_cndmask_b32_e32 v142, v226, v233, vcc
	v_add_u32_e32 v236, 13, v170
	v_cmp_gt_u32_e32 vcc, s15, v236
	v_fmac_f32_e32 v234, 0x3e38aa3b, v138
	s_nop 0
	v_cndmask_b32_e32 v137, v226, v234, vcc
	v_add_u32_e32 v236, 12, v170
	v_cmp_gt_u32_e32 vcc, s15, v236
	v_fmac_f32_e32 v235, 0x3e38aa3b, v139
	s_nop 0
	v_cndmask_b32_e32 v136, v226, v235, vcc
	v_max3_f32 v138, v173, s86, v172
	v_max3_f32 v138, v138, v141, v140
	v_cmp_lt_i32_e32 vcc, v223, v218
	v_max3_f32 v138, v138, v143, v142
	v_max3_f32 v138, v138, v137, v136
	v_cndmask_b32_e32 v139, v217, v223, vcc
	v_lshlrev_b32_e32 v139, 2, v139
	ds_bpermute_b32 v139, v139, v138
	v_cmp_lt_i32_e32 vcc, v224, v218
	s_waitcnt lgkmcnt(0)
	v_max_f32_e32 v139, v139, v139
	v_max_f32_e32 v138, v138, v139
	v_cndmask_b32_e32 v139, v217, v224, vcc
	v_lshlrev_b32_e32 v139, 2, v139
	ds_bpermute_b32 v139, v139, v138
	s_waitcnt lgkmcnt(0)
	v_max3_f32 v174, v163, v138, v139
	v_sub_f32_e32 v139, v173, v174
	v_exp_f32_e32 v139, v139
	v_sub_f32_e32 v172, v172, v174
	v_exp_f32_e32 v172, v172
	v_sub_f32_e32 v141, v141, v174
	v_exp_f32_e32 v141, v141
	v_sub_f32_e32 v140, v140, v174
	v_exp_f32_e32 v140, v140
	v_sub_f32_e32 v143, v143, v174
	v_sub_f32_e32 v138, v163, v174
	v_add_f32_e32 v163, 0, v139
	v_exp_f32_e32 v143, v143
	v_sub_f32_e32 v142, v142, v174
	v_add_f32_e32 v163, v172, v163
	v_exp_f32_e32 v142, v142
	v_sub_f32_e32 v137, v137, v174
	v_add_f32_e32 v163, v141, v163
	v_exp_f32_e32 v173, v137
	v_add_f32_e32 v163, v140, v163
	v_add_f32_e32 v163, v143, v163
	v_add_f32_e32 v163, v142, v163
	v_sub_f32_e32 v136, v136, v174
	v_add_f32_e32 v137, v173, v163
	v_exp_f32_e32 v163, v136
	v_exp_f32_e32 v136, v138
	v_cvt_pk_bf16_f32 v138, v143, v142
	v_add_f32_e32 v175, v163, v137
	v_fmac_f32_e32 v175, v164, v136
	v_pk_mul_f32 v[58:59], v[58:59], v[136:137] op_sel_hi:[1,0]
	v_pk_mul_f32 v[56:57], v[56:57], v[136:137] op_sel_hi:[1,0]
	v_pk_mul_f32 v[62:63], v[62:63], v[136:137] op_sel_hi:[1,0]
	v_pk_mul_f32 v[60:61], v[60:61], v[136:137] op_sel_hi:[1,0]
	v_pk_mul_f32 v[66:67], v[66:67], v[136:137] op_sel_hi:[1,0]
	v_pk_mul_f32 v[64:65], v[64:65], v[136:137] op_sel_hi:[1,0]
	v_pk_mul_f32 v[70:71], v[70:71], v[136:137] op_sel_hi:[1,0]
	v_pk_mul_f32 v[68:69], v[68:69], v[136:137] op_sel_hi:[1,0]
	v_cvt_pk_bf16_f32 v136, v139, v172
	v_cvt_pk_bf16_f32 v137, v141, v140
	v_cvt_pk_bf16_f32 v139, v173, v163
	v_mov_b32_e32 v164, v175
	v_mov_b32_e32 v163, v174
	v_mfma_f32_16x16x32_bf16 v[56:59], v[116:119], v[136:139], v[56:59]
	v_mfma_f32_16x16x32_bf16 v[60:63], v[112:115], v[136:139], v[60:63]
	v_mfma_f32_16x16x32_bf16 v[64:67], v[108:111], v[136:139], v[64:67]
	v_mfma_f32_16x16x32_bf16 v[68:71], v[104:107], v[136:139], v[68:71]
	s_and_b64 vcc, exec, s[4:5]
	s_cbranch_vccnz .LBB0_262
; template <int MODE>
; __device__ __forceinline__ void attn_wave(LAS unsigned char* lds, const bf16_t* qkv, bf16_t* Yout, const float* sinks, int wi) {
;     ...
;             const int dbase = q0 + QSTEP * qt + c - k0 - 4 * g;
;             if (MODE == MODE_A) {
;                 float mx = -1e30f;
; #pragma unroll
;                 for (int nt = 0; nt < 2; ++nt)
; #pragma unroll
;                     for (int j = 0; j < 4; ++j) { const int dist = dbase - (16 * nt + j); const bool valid = (unsigned)dist < 128u;
;                         const float bias2 = lutp[qt * HSTEP * 128 + (dist & 127)];
;                         const float lg = valid ? (s[nt][j] * C1 + bias2) : -1e30f; s[nt][j] = lg; mx = fmaxf(mx, lg); }
;                 mx = fmaxf(mx, __shfl_xor(mx, 16)); mx = fmaxf(mx, __shfl_xor(mx, 32));
;                 const float mnew = fmaxf(mrun[qt], mx); const float alpha = __builtin_amdgcn_exp2f(mrun[qt] - mnew); mrun[qt] = mnew;
;                 float ps = 0.f;
; #pragma unroll
;                 for (int nt = 0; nt < 2; ++nt)
; #pragma unroll
;                     for (int j = 0; j < 4; ++j) { const float p = __builtin_amdgcn_exp2f(s[nt][j] - mnew); s[nt][j] = p; ps += p; }
;                 lrun[qt] = lrun[qt] * alpha + ps;
; #pragma unroll
;                 for (int dt = 0; dt < 4; ++dt) o[qt][dt] = o[qt][dt] * alpha;
.LBB0_281:
	s_waitcnt vmcnt(3)
	v_mfma_f32_16x16x32_bf16 v[136:139], v[120:123], v[80:83], 0
	s_waitcnt vmcnt(2)
	v_mfma_f32_16x16x32_bf16 v[140:143], v[124:127], v[84:87], v[136:139]
	s_waitcnt vmcnt(1)
	v_mfma_f32_16x16x32_bf16 v[136:139], v[132:135], v[80:83], 0
	s_waitcnt vmcnt(0)
	v_mfma_f32_16x16x32_bf16 v[136:139], v[128:131], v[84:87], v[136:139]
	v_add_u32_e32 v228, s19, v167
	v_add_u32_e32 v228, 0x12200, v228
	ds_read_b32 v228, v228
	v_add_u32_e32 v229, s19, v167
	v_add_u32_e32 v229, 0x121fc, v229
	ds_read_b32 v229, v229
	v_add_u32_e32 v230, s19, v167
	v_add_u32_e32 v230, 0x121f8, v230
	ds_read_b32 v230, v230
	v_add_u32_e32 v231, s19, v167
	v_add_u32_e32 v231, 0x121f4, v231
	ds_read_b32 v231, v231
	v_add_u32_e32 v232, s19, v167
	v_add_u32_e32 v232, 0x121c0, v232
	ds_read_b32 v232, v232
	v_add_u32_e32 v233, s19, v165
	v_add_u32_e32 v233, 0x121bc, v233
	ds_read_b32 v233, v233
	v_add_u32_e32 v234, s19, v165
	v_add_u32_e32 v234, 0x121b8, v234
	ds_read_b32 v234, v234
	v_add_u32_e32 v235, s19, v165
	v_add_u32_e32 v235, 0x121b4, v235
	ds_read_b32 v235, v235
	s_waitcnt lgkmcnt(0)
	v_cmp_gt_u32_e32 vcc, s15, v171
	v_fmac_f32_e32 v228, 0x3e38aa3b, v140
	s_nop 0
	v_cndmask_b32_e32 v173, v226, v228, vcc
	v_add_u32_e32 v236, 30, v170
	v_cmp_gt_u32_e32 vcc, s15, v236
	v_fmac_f32_e32 v229, 0x3e38aa3b, v141
	s_nop 0
	v_cndmask_b32_e32 v172, v226, v229, vcc
	v_add_u32_e32 v236, 29, v170
	v_cmp_gt_u32_e32 vcc, s15, v236
	v_fmac_f32_e32 v230, 0x3e38aa3b, v142
	s_nop 0
	v_cndmask_b32_e32 v141, v226, v230, vcc
	v_add_u32_e32 v236, 28, v170
	v_cmp_gt_u32_e32 vcc, s15, v236
	v_fmac_f32_e32 v231, 0x3e38aa3b, v143
	s_nop 0
	v_cndmask_b32_e32 v140, v226, v231, vcc
	v_add_u32_e32 v236, 15, v170
	v_cmp_gt_u32_e32 vcc, s15, v236
	v_fmac_f32_e32 v232, 0x3e38aa3b, v136
	s_nop 0
	v_cndmask_b32_e32 v143, v226, v232, vcc
	v_add_u32_e32 v236, 14, v170
	v_cmp_gt_u32_e32 vcc, s15, v236
	v_fmac_f32_e32 v233, 0x3e38aa3b, v137
	s_nop 0
	v_cndmask_b32_e32 v142, v226, v233, vcc
	v_add_u32_e32 v236, 13, v170
	v_cmp_gt_u32_e32 vcc, s15, v236
	v_fmac_f32_e32 v234, 0x3e38aa3b, v138
	s_nop 0
	v_cndmask_b32_e32 v137, v226, v234, vcc
	v_add_u32_e32 v236, 12, v170
	v_cmp_gt_u32_e32 vcc, s15, v236
	v_fmac_f32_e32 v235, 0x3e38aa3b, v139
	s_nop 0
	v_cndmask_b32_e32 v136, v226, v235, vcc
	v_max3_f32 v138, v173, s86, v172
	v_max3_f32 v138, v138, v141, v140
	v_cmp_lt_i32_e32 vcc, v223, v218
	v_max3_f32 v138, v138, v143, v142
	v_max3_f32 v138, v138, v137, v136
	v_cndmask_b32_e32 v139, v217, v223, vcc
	v_lshlrev_b32_e32 v139, 2, v139
	ds_bpermute_b32 v139, v139, v138
	v_cmp_lt_i32_e32 vcc, v224, v218
	s_waitcnt lgkmcnt(0)
	v_max_f32_e32 v139, v139, v139
	v_max_f32_e32 v138, v138, v139
	v_cndmask_b32_e32 v139, v217, v224, vcc
	v_lshlrev_b32_e32 v139, 2, v139
	ds_bpermute_b32 v139, v139, v138
	s_waitcnt lgkmcnt(0)
	v_max3_f32 v174, v162, v138, v139
	v_sub_f32_e32 v139, v173, v174
	v_exp_f32_e32 v139, v139
	v_sub_f32_e32 v172, v172, v174
	v_exp_f32_e32 v172, v172
	v_sub_f32_e32 v141, v141, v174
	v_exp_f32_e32 v141, v141
	v_sub_f32_e32 v140, v140, v174
	v_exp_f32_e32 v140, v140
	v_sub_f32_e32 v143, v143, v174
	v_sub_f32_e32 v138, v162, v174
	v_add_f32_e32 v162, 0, v139
	v_exp_f32_e32 v143, v143
	v_sub_f32_e32 v142, v142, v174
	v_add_f32_e32 v162, v172, v162
	v_exp_f32_e32 v142, v142
	v_sub_f32_e32 v137, v137, v174
	v_add_f32_e32 v162, v141, v162
	v_exp_f32_e32 v173, v137
	v_add_f32_e32 v162, v140, v162
	v_add_f32_e32 v162, v143, v162
	v_add_f32_e32 v162, v142, v162
	v_sub_f32_e32 v136, v136, v174
	v_add_f32_e32 v137, v173, v162
	v_exp_f32_e32 v162, v136
	v_exp_f32_e32 v136, v138
	v_cvt_pk_bf16_f32 v138, v143, v142
	v_add_f32_e32 v175, v162, v137
	v_fmac_f32_e32 v175, v161, v136
	v_pk_mul_f32 v[42:43], v[42:43], v[136:137] op_sel_hi:[1,0]
	v_pk_mul_f32 v[40:41], v[40:41], v[136:137] op_sel_hi:[1,0]
	v_pk_mul_f32 v[46:47], v[46:47], v[136:137] op_sel_hi:[1,0]
	v_pk_mul_f32 v[44:45], v[44:45], v[136:137] op_sel_hi:[1,0]
	v_pk_mul_f32 v[50:51], v[50:51], v[136:137] op_sel_hi:[1,0]
	v_pk_mul_f32 v[48:49], v[48:49], v[136:137] op_sel_hi:[1,0]
	v_pk_mul_f32 v[54:55], v[54:55], v[136:137] op_sel_hi:[1,0]
	v_pk_mul_f32 v[52:53], v[52:53], v[136:137] op_sel_hi:[1,0]
	v_cvt_pk_bf16_f32 v136, v139, v172
	v_cvt_pk_bf16_f32 v137, v141, v140
	v_cvt_pk_bf16_f32 v139, v173, v162
	v_mov_b32_e32 v161, v175
	v_mov_b32_e32 v162, v174
	v_mfma_f32_16x16x32_bf16 v[40:43], v[116:119], v[136:139], v[40:43]
	v_mfma_f32_16x16x32_bf16 v[44:47], v[112:115], v[136:139], v[44:47]
	v_mfma_f32_16x16x32_bf16 v[48:51], v[108:111], v[136:139], v[48:51]
	v_mfma_f32_16x16x32_bf16 v[52:55], v[104:107], v[136:139], v[52:55]
	s_and_b64 vcc, exec, s[4:5]
	s_cbranch_vccnz .LBB0_263
; template <int MODE>
; __device__ __forceinline__ void attn_wave(LAS unsigned char* lds, const bf16_t* qkv, bf16_t* Yout, const float* sinks, int wi) {
;     ...
;             const int dbase = q0 + QSTEP * qt + c - k0 - 4 * g;
;             if (MODE == MODE_A) {
;                 float mx = -1e30f;
; #pragma unroll
;                 for (int nt = 0; nt < 2; ++nt)
; #pragma unroll
;                     for (int j = 0; j < 4; ++j) { const int dist = dbase - (16 * nt + j); const bool valid = (unsigned)dist < 128u;
;                         const float bias2 = lutp[qt * HSTEP * 128 + (dist & 127)];
;                         const float lg = valid ? (s[nt][j] * C1 + bias2) : -1e30f; s[nt][j] = lg; mx = fmaxf(mx, lg); }
;                 mx = fmaxf(mx, __shfl_xor(mx, 16)); mx = fmaxf(mx, __shfl_xor(mx, 32));
;                 const float mnew = fmaxf(mrun[qt], mx); const float alpha = __builtin_amdgcn_exp2f(mrun[qt] - mnew); mrun[qt] = mnew;
;                 float ps = 0.f;
; #pragma unroll
;                 for (int nt = 0; nt < 2; ++nt)
; #pragma unroll
;                     for (int j = 0; j < 4; ++j) { const float p = __builtin_amdgcn_exp2f(s[nt][j] - mnew); s[nt][j] = p; ps += p; }
;                 lrun[qt] = lrun[qt] * alpha + ps;
; #pragma unroll
;                 for (int dt = 0; dt < 4; ++dt) o[qt][dt] = o[qt][dt] * alpha;
.LBB0_298:
	s_waitcnt vmcnt(3)
	v_mfma_f32_16x16x32_bf16 v[136:139], v[120:123], v[88:91], 0
	s_waitcnt vmcnt(2)
	v_mfma_f32_16x16x32_bf16 v[140:143], v[124:127], v[92:95], v[136:139]
	s_waitcnt vmcnt(1)
	v_mfma_f32_16x16x32_bf16 v[136:139], v[132:135], v[88:91], 0
	s_waitcnt vmcnt(0)
	v_mfma_f32_16x16x32_bf16 v[136:139], v[128:131], v[92:95], v[136:139]
	v_add_u32_e32 v228, s19, v167
	v_add_u32_e32 v228, 0x12400, v228
	ds_read_b32 v228, v228
	v_add_u32_e32 v229, s19, v167
	v_add_u32_e32 v229, 0x123fc, v229
	ds_read_b32 v229, v229
	v_add_u32_e32 v230, s19, v167
	v_add_u32_e32 v230, 0x123f8, v230
	ds_read_b32 v230, v230
	v_add_u32_e32 v231, s19, v167
	v_add_u32_e32 v231, 0x123f4, v231
	ds_read_b32 v231, v231
	v_add_u32_e32 v232, s19, v167
	v_add_u32_e32 v232, 0x123c0, v232
	ds_read_b32 v232, v232
	v_add_u32_e32 v233, s19, v165
	v_add_u32_e32 v233, 0x123bc, v233
	ds_read_b32 v233, v233
	v_add_u32_e32 v234, s19, v165
	v_add_u32_e32 v234, 0x123b8, v234
	ds_read_b32 v234, v234
	v_add_u32_e32 v235, s19, v165
	v_add_u32_e32 v235, 0x123b4, v235
	ds_read_b32 v235, v235
	s_waitcnt lgkmcnt(0)
	v_cmp_gt_u32_e32 vcc, s15, v171
	v_fmac_f32_e32 v228, 0x3e38aa3b, v140
	s_nop 0
	v_cndmask_b32_e32 v173, v226, v228, vcc
	v_add_u32_e32 v236, 30, v170
	v_cmp_gt_u32_e32 vcc, s15, v236
	v_fmac_f32_e32 v229, 0x3e38aa3b, v141
	s_nop 0
	v_cndmask_b32_e32 v172, v226, v229, vcc
	v_add_u32_e32 v236, 29, v170
	v_cmp_gt_u32_e32 vcc, s15, v236
	v_fmac_f32_e32 v230, 0x3e38aa3b, v142
	s_nop 0
	v_cndmask_b32_e32 v141, v226, v230, vcc
	v_add_u32_e32 v236, 28, v170
	v_cmp_gt_u32_e32 vcc, s15, v236
	v_fmac_f32_e32 v231, 0x3e38aa3b, v143
	s_nop 0
	v_cndmask_b32_e32 v140, v226, v231, vcc
	v_add_u32_e32 v236, 15, v170
	v_cmp_gt_u32_e32 vcc, s15, v236
	v_fmac_f32_e32 v232, 0x3e38aa3b, v136
	s_nop 0
	v_cndmask_b32_e32 v143, v226, v232, vcc
	v_add_u32_e32 v236, 14, v170
	v_cmp_gt_u32_e32 vcc, s15, v236
	v_fmac_f32_e32 v233, 0x3e38aa3b, v137
	s_nop 0
	v_cndmask_b32_e32 v142, v226, v233, vcc
	v_add_u32_e32 v236, 13, v170
	v_cmp_gt_u32_e32 vcc, s15, v236
	v_fmac_f32_e32 v234, 0x3e38aa3b, v138
	s_nop 0
	v_cndmask_b32_e32 v137, v226, v234, vcc
	v_add_u32_e32 v236, 12, v170
	v_cmp_gt_u32_e32 vcc, s15, v236
	v_fmac_f32_e32 v235, 0x3e38aa3b, v139
	s_nop 0
	v_cndmask_b32_e32 v136, v226, v235, vcc
	v_max3_f32 v138, v173, s86, v172
	v_max3_f32 v138, v138, v141, v140
	v_cmp_lt_i32_e32 vcc, v223, v218
	v_max3_f32 v138, v138, v143, v142
	v_max3_f32 v138, v138, v137, v136
	v_cndmask_b32_e32 v139, v217, v223, vcc
	v_lshlrev_b32_e32 v139, 2, v139
	ds_bpermute_b32 v139, v139, v138
	v_cmp_lt_i32_e32 vcc, v224, v218
	s_waitcnt lgkmcnt(0)
	v_max_f32_e32 v139, v139, v139
	v_max_f32_e32 v138, v138, v139
	v_cndmask_b32_e32 v139, v217, v224, vcc
	v_lshlrev_b32_e32 v139, 2, v139
	ds_bpermute_b32 v139, v139, v138
	s_waitcnt lgkmcnt(0)
	v_max3_f32 v174, v159, v138, v139
	v_sub_f32_e32 v139, v173, v174
	v_exp_f32_e32 v139, v139
	v_sub_f32_e32 v172, v172, v174
	v_exp_f32_e32 v172, v172
	v_sub_f32_e32 v141, v141, v174
	v_exp_f32_e32 v141, v141
	v_sub_f32_e32 v140, v140, v174
	v_exp_f32_e32 v140, v140
	v_sub_f32_e32 v143, v143, v174
	v_sub_f32_e32 v138, v159, v174
	v_add_f32_e32 v159, 0, v139
	v_exp_f32_e32 v143, v143
	v_sub_f32_e32 v142, v142, v174
	v_add_f32_e32 v159, v172, v159
	v_exp_f32_e32 v142, v142
	v_sub_f32_e32 v137, v137, v174
	v_add_f32_e32 v159, v141, v159
	v_exp_f32_e32 v173, v137
	v_add_f32_e32 v159, v140, v159
	v_add_f32_e32 v159, v143, v159
	v_add_f32_e32 v159, v142, v159
	v_sub_f32_e32 v136, v136, v174
	v_add_f32_e32 v137, v173, v159
	v_exp_f32_e32 v159, v136
	v_exp_f32_e32 v136, v138
	v_cvt_pk_bf16_f32 v138, v143, v142
	v_add_f32_e32 v175, v159, v137
	v_fmac_f32_e32 v175, v158, v136
	v_pk_mul_f32 v[26:27], v[26:27], v[136:137] op_sel_hi:[1,0]
	v_pk_mul_f32 v[24:25], v[24:25], v[136:137] op_sel_hi:[1,0]
	v_pk_mul_f32 v[30:31], v[30:31], v[136:137] op_sel_hi:[1,0]
	v_pk_mul_f32 v[28:29], v[28:29], v[136:137] op_sel_hi:[1,0]
	v_pk_mul_f32 v[34:35], v[34:35], v[136:137] op_sel_hi:[1,0]
	v_pk_mul_f32 v[32:33], v[32:33], v[136:137] op_sel_hi:[1,0]
	v_pk_mul_f32 v[38:39], v[38:39], v[136:137] op_sel_hi:[1,0]
	v_pk_mul_f32 v[36:37], v[36:37], v[136:137] op_sel_hi:[1,0]
	v_cvt_pk_bf16_f32 v136, v139, v172
	v_cvt_pk_bf16_f32 v137, v141, v140
	v_cvt_pk_bf16_f32 v139, v173, v159
	v_mov_b32_e32 v158, v175
	v_mov_b32_e32 v159, v174
	v_mfma_f32_16x16x32_bf16 v[24:27], v[116:119], v[136:139], v[24:27]
	v_mfma_f32_16x16x32_bf16 v[28:31], v[112:115], v[136:139], v[28:31]
	v_mfma_f32_16x16x32_bf16 v[32:35], v[108:111], v[136:139], v[32:35]
	v_mfma_f32_16x16x32_bf16 v[36:39], v[104:107], v[136:139], v[36:39]
	s_and_b64 vcc, exec, s[4:5]
	s_cbranch_vccnz .LBB0_259
